# fox steady-state loop: the decay-table reads that prefill the next tile's accumulators are issued before the per-tile barrier (their LDS latency overlaps the barrier) for the mid-body barrier
# speedup vs baseline: 1.0024x; 1.0017x over previous
.LBB0_672:
	s_mov_b32 s28, s34
	s_mov_b32 s34, s27
	ds_read_b128 v[66:69], v166
	ds_read_b128 v[70:73], v166 offset:32
	ds_read_b128 v[74:77], v166 offset:64
	ds_read_b128 v[78:81], v166 offset:96
	ds_read_b128 v[162:165], v166 offset:128
	ds_read_b128 v[168:171], v166 offset:160
	ds_read_b128 v[244:247], v166 offset:192
	ds_read_b128 v[248:251], v166 offset:224
	s_waitcnt lgkmcnt(4)
	v_sub_f32_e32 v97, v81, v242
	v_sub_f32_e32 v96, v80, v242
	v_sub_f32_e32 v95, v79, v242
	v_sub_f32_e32 v94, v78, v242
	v_sub_f32_e32 v93, v77, v242
	v_sub_f32_e32 v92, v76, v242
	v_sub_f32_e32 v91, v75, v242
	v_sub_f32_e32 v90, v74, v242
	v_sub_f32_e32 v89, v73, v242
	v_sub_f32_e32 v88, v72, v242
	v_sub_f32_e32 v87, v71, v242
	v_sub_f32_e32 v86, v70, v242
	v_sub_f32_e32 v85, v69, v242
	v_sub_f32_e32 v84, v68, v242
	v_sub_f32_e32 v83, v67, v242
	v_sub_f32_e32 v82, v66, v242
	s_waitcnt lgkmcnt(0)
	v_sub_f32_e32 v81, v251, v242
	v_sub_f32_e32 v80, v250, v242
	v_sub_f32_e32 v79, v249, v242
	v_sub_f32_e32 v78, v248, v242
	v_sub_f32_e32 v77, v247, v242
	v_sub_f32_e32 v76, v246, v242
	v_sub_f32_e32 v75, v245, v242
	v_sub_f32_e32 v74, v244, v242
	v_sub_f32_e32 v73, v171, v242
	v_sub_f32_e32 v72, v170, v242
	v_sub_f32_e32 v71, v169, v242
	v_sub_f32_e32 v70, v168, v242
	v_sub_f32_e32 v69, v165, v242
	v_sub_f32_e32 v68, v164, v242
	v_sub_f32_e32 v67, v163, v242
	v_sub_f32_e32 v66, v162, v242
	v_add_u32_e32 v167, s35, v194
	ds_read_b64_tr_b16 v[162:163], v167 offset:24576
	ds_read_b64_tr_b16 v[164:165], v167 offset:25088
	v_add_f32_e32 v110, v50, v51
	v_add_f32_e32 v110, v52, v110
	v_add_f32_e32 v110, v53, v110
	v_add_f32_e32 v110, v54, v110
	v_add_f32_e32 v110, v55, v110
	v_cvt_pk_bf16_f32 v126, v50, v51
	v_cvt_pk_bf16_f32 v127, v52, v53
	v_mfma_f32_32x32x16_bf16 v[82:97], v[158:161], v[114:117], v[82:97]
	ds_read_b64_tr_b16 v[50:51], v167 offset:28672
	ds_read_b64_tr_b16 v[52:53], v167 offset:29184
	v_add_f32_e32 v110, v56, v110
	v_add_f32_e32 v110, v57, v110
	v_add_f32_e32 v110, v58, v110
	v_add_f32_e32 v110, v59, v110
	v_cvt_pk_bf16_f32 v128, v54, v55
	v_cvt_pk_bf16_f32 v129, v56, v57
	v_mfma_f32_32x32x16_bf16 v[66:81], v[154:157], v[114:117], v[66:81]
	ds_read_b64_tr_b16 v[54:55], v167 offset:25600
	ds_read_b64_tr_b16 v[56:57], v167 offset:26112
	v_add_f32_e32 v110, v60, v110
	v_add_f32_e32 v110, v61, v110
	v_add_f32_e32 v110, v62, v110
	v_add_f32_e32 v110, v63, v110
	v_cvt_pk_bf16_f32 v122, v58, v59
	v_cvt_pk_bf16_f32 v123, v60, v61
	v_mfma_f32_32x32x16_bf16 v[82:97], v[150:153], v[106:109], v[82:97]
	ds_read_b64_tr_b16 v[58:59], v167 offset:29696
	ds_read_b64_tr_b16 v[60:61], v167 offset:30208
	v_add_f32_e32 v110, v64, v110
	v_add_f32_e32 v110, v65, v110
	v_add_f32_e32 v110, v34, v110
	v_add_f32_e32 v110, v35, v110
	v_cvt_pk_bf16_f32 v124, v62, v63
	v_cvt_pk_bf16_f32 v125, v64, v65
	v_mfma_f32_32x32x16_bf16 v[66:81], v[146:149], v[106:109], v[66:81]
	ds_read_b64_tr_b16 v[62:63], v167 offset:26624
	ds_read_b64_tr_b16 v[64:65], v167 offset:27136
	v_add_f32_e32 v110, v36, v110
	v_add_f32_e32 v110, v37, v110
	v_add_f32_e32 v110, v38, v110
	v_add_f32_e32 v110, v39, v110
	v_cvt_pk_bf16_f32 v118, v34, v35
	v_cvt_pk_bf16_f32 v119, v36, v37
	v_mfma_f32_32x32x16_bf16 v[82:97], v[142:145], v[102:105], v[82:97]
	ds_read_b64_tr_b16 v[34:35], v167 offset:30720
	ds_read_b64_tr_b16 v[36:37], v167 offset:31232
	v_add_f32_e32 v110, v40, v110
	v_add_f32_e32 v110, v41, v110
	v_add_f32_e32 v110, v42, v110
	v_add_f32_e32 v110, v43, v110
	v_cvt_pk_bf16_f32 v120, v38, v39
	v_cvt_pk_bf16_f32 v121, v40, v41
	v_mfma_f32_32x32x16_bf16 v[66:81], v[138:141], v[102:105], v[66:81]
	ds_read_b64_tr_b16 v[38:39], v167 offset:27648
	ds_read_b64_tr_b16 v[40:41], v167 offset:28160
	v_add_f32_e32 v110, v44, v110
	v_add_f32_e32 v110, v45, v110
	v_add_f32_e32 v110, v46, v110
	v_mfma_f32_32x32x16_bf16 v[82:97], v[134:137], v[98:101], v[82:97]
	v_add_f32_e32 v134, v47, v110
	v_cvt_pk_bf16_f32 v110, v42, v43
	v_cvt_pk_bf16_f32 v111, v44, v45
	ds_read_b64_tr_b16 v[42:43], v167 offset:31744
	ds_read_b64_tr_b16 v[44:45], v167 offset:32256
	v_add_f32_e32 v112, v48, v134
	v_add_f32_e32 v112, v49, v112
	v_mfma_f32_32x32x16_bf16 v[66:81], v[130:133], v[98:101], v[66:81]
	v_add_f32_e32 v130, 0, v112
	v_cvt_pk_bf16_f32 v112, v46, v47
	v_cvt_pk_bf16_f32 v113, v48, v49
	s_add_u32 s36, s12, 0xfffa0000
	s_addc_u32 s37, s13, -1
	s_add_i32 s27, s27, s84
	s_mov_b32 s35, m0
	s_mov_b32 m0, s27
	s_nop 0
	global_load_lds_dwordx4 v191, s[36:37]
	s_mov_b32 m0, s35
	s_add_u32 s36, s10, 0xfffa0000
	s_addc_u32 s37, s11, -1
	s_add_i32 s27, s28, s85
	s_mov_b32 s35, m0
	s_mov_b32 m0, s27
	s_nop 0
	global_load_lds_dwordx4 v192, s[36:37]
	s_mov_b32 m0, s35
	v_add_f32_e32 v167, v243, v130
	s_waitcnt lgkmcnt(14)
	v_mfma_f32_32x32x16_bf16 v[2:17], v[126:129], v[162:165], v[2:17]
	v_exp_f32_e32 v82, v82
	v_exp_f32_e32 v83, v83
	v_exp_f32_e32 v84, v84
	v_exp_f32_e32 v85, v85
	s_waitcnt lgkmcnt(12)
	v_mfma_f32_32x32x16_bf16 v[18:33], v[126:129], v[50:53], v[18:33]
	v_exp_f32_e32 v86, v86
	v_exp_f32_e32 v87, v87
	v_exp_f32_e32 v88, v88
	v_exp_f32_e32 v89, v89
	v_add_u32_e32 v46, s28, v193
	ds_read_b128 v[162:165], v46
	ds_read_b128 v[154:157], v46 offset:512
	s_waitcnt lgkmcnt(12)
	v_mfma_f32_32x32x16_bf16 v[2:17], v[122:125], v[54:57], v[2:17]
	v_exp_f32_e32 v90, v90
	v_exp_f32_e32 v91, v91
	v_exp_f32_e32 v92, v92
	v_exp_f32_e32 v93, v93
	ds_read_b128 v[150:153], v46 offset:2048
	ds_read_b128 v[146:149], v46 offset:2560
	s_waitcnt lgkmcnt(12)
	v_mfma_f32_32x32x16_bf16 v[18:33], v[122:125], v[58:61], v[18:33]
	v_exp_f32_e32 v94, v94
	v_exp_f32_e32 v95, v95
	v_exp_f32_e32 v96, v96
	v_exp_f32_e32 v97, v97
	ds_read_b128 v[142:145], v46 offset:4096
	ds_read_b128 v[138:141], v46 offset:4608
	s_waitcnt lgkmcnt(12)
	v_mfma_f32_32x32x16_bf16 v[2:17], v[118:121], v[62:65], v[2:17]
	v_exp_f32_e32 v66, v66
	v_exp_f32_e32 v67, v67
	v_exp_f32_e32 v68, v68
	v_exp_f32_e32 v69, v69
	ds_read_b128 v[134:137], v46 offset:6144
	ds_read_b128 v[130:133], v46 offset:6656
	s_waitcnt lgkmcnt(12)
	v_mfma_f32_32x32x16_bf16 v[18:33], v[118:121], v[34:37], v[18:33]
	v_exp_f32_e32 v70, v70
	v_exp_f32_e32 v71, v71
	v_exp_f32_e32 v72, v72
	v_exp_f32_e32 v73, v73
	s_waitcnt lgkmcnt(10)
	v_mfma_f32_32x32x16_bf16 v[2:17], v[110:113], v[38:41], v[2:17]
	v_exp_f32_e32 v74, v74
	v_exp_f32_e32 v75, v75
	v_exp_f32_e32 v76, v76
	v_exp_f32_e32 v77, v77
	s_waitcnt lgkmcnt(8)
	v_mfma_f32_32x32x16_bf16 v[18:33], v[110:113], v[42:45], v[18:33]
	v_exp_f32_e32 v78, v78
	v_exp_f32_e32 v79, v79
	v_exp_f32_e32 v80, v80
	v_exp_f32_e32 v81, v81
	ds_read_b128 v[34:37], v166 offset:256
	ds_read_b128 v[38:41], v166 offset:288
	ds_read_b128 v[42:45], v166 offset:320
	ds_read_b128 v[46:49], v166 offset:352
	ds_read_b128 v[158:161], v166 offset:384
	ds_read_b128 v[168:171], v166 offset:416
	ds_read_b128 v[244:247], v166 offset:448
	ds_read_b128 v[248:251], v166 offset:480
	s_waitcnt vmcnt(2) lgkmcnt(8)
	s_barrier
	s_add_i32 s27, s28, 0x2000
	s_cmpk_lg_i32 s28, 0x4000
	s_cselect_b32 s27, s27, 0
	s_waitcnt lgkmcnt(4)
	v_sub_f32_e32 v65, v49, v242
	v_sub_f32_e32 v64, v48, v242
	v_sub_f32_e32 v63, v47, v242
	v_sub_f32_e32 v62, v46, v242
	v_sub_f32_e32 v61, v45, v242
	v_sub_f32_e32 v60, v44, v242
	v_sub_f32_e32 v59, v43, v242
	v_sub_f32_e32 v58, v42, v242
	v_sub_f32_e32 v57, v41, v242
	v_sub_f32_e32 v56, v40, v242
	v_sub_f32_e32 v55, v39, v242
	v_sub_f32_e32 v54, v38, v242
	v_sub_f32_e32 v53, v37, v242
	v_sub_f32_e32 v52, v36, v242
	v_sub_f32_e32 v51, v35, v242
	v_sub_f32_e32 v50, v34, v242
	s_waitcnt lgkmcnt(0)
	v_sub_f32_e32 v49, v251, v242
	v_sub_f32_e32 v48, v250, v242
	v_sub_f32_e32 v47, v249, v242
	v_sub_f32_e32 v46, v248, v242
	v_sub_f32_e32 v45, v247, v242
	v_sub_f32_e32 v44, v246, v242
	v_sub_f32_e32 v43, v245, v242
	v_sub_f32_e32 v42, v244, v242
	v_sub_f32_e32 v41, v171, v242
	v_sub_f32_e32 v40, v170, v242
	v_sub_f32_e32 v39, v169, v242
	v_sub_f32_e32 v38, v168, v242
	v_sub_f32_e32 v37, v161, v242
	v_sub_f32_e32 v36, v160, v242
	v_sub_f32_e32 v35, v159, v242
	v_sub_f32_e32 v34, v158, v242
	v_add_u32_e32 v172, s34, v194
	ds_read_b64_tr_b16 v[158:159], v172 offset:24576
	ds_read_b64_tr_b16 v[160:161], v172 offset:25088
	v_mfma_f32_32x32x16_bf16 v[50:65], v[162:165], v[114:117], v[50:65]
	v_add_f32_e32 v110, v82, v83
	v_add_f32_e32 v110, v84, v110
	v_add_f32_e32 v110, v85, v110
	v_add_f32_e32 v110, v86, v110
	v_add_f32_e32 v110, v87, v110
	v_cvt_pk_bf16_f32 v126, v82, v83
	v_cvt_pk_bf16_f32 v127, v84, v85
	ds_read_b64_tr_b16 v[82:83], v172 offset:28672
	ds_read_b64_tr_b16 v[84:85], v172 offset:29184
	v_mfma_f32_32x32x16_bf16 v[34:49], v[154:157], v[114:117], v[34:49]
	v_add_f32_e32 v110, v88, v110
	v_add_f32_e32 v110, v89, v110
	v_add_f32_e32 v110, v90, v110
	v_add_f32_e32 v110, v91, v110
	v_cvt_pk_bf16_f32 v128, v86, v87
	v_cvt_pk_bf16_f32 v129, v88, v89
	ds_read_b64_tr_b16 v[86:87], v172 offset:25600
	ds_read_b64_tr_b16 v[88:89], v172 offset:26112
	v_mfma_f32_32x32x16_bf16 v[50:65], v[150:153], v[106:109], v[50:65]
	v_add_f32_e32 v110, v92, v110
	v_add_f32_e32 v110, v93, v110
	v_add_f32_e32 v110, v94, v110
	v_add_f32_e32 v110, v95, v110
	v_cvt_pk_bf16_f32 v122, v90, v91
	v_cvt_pk_bf16_f32 v123, v92, v93
	ds_read_b64_tr_b16 v[90:91], v172 offset:29696
	ds_read_b64_tr_b16 v[92:93], v172 offset:30208
	v_mfma_f32_32x32x16_bf16 v[34:49], v[146:149], v[106:109], v[34:49]
	v_add_f32_e32 v110, v96, v110
	v_add_f32_e32 v110, v97, v110
	v_add_f32_e32 v110, v66, v110
	v_add_f32_e32 v110, v67, v110
	v_cvt_pk_bf16_f32 v124, v94, v95
	v_cvt_pk_bf16_f32 v125, v96, v97
	ds_read_b64_tr_b16 v[94:95], v172 offset:26624
	ds_read_b64_tr_b16 v[96:97], v172 offset:27136
	v_mfma_f32_32x32x16_bf16 v[50:65], v[142:145], v[102:105], v[50:65]
	v_add_f32_e32 v110, v68, v110
	v_add_f32_e32 v110, v69, v110
	v_add_f32_e32 v110, v70, v110
	v_add_f32_e32 v110, v71, v110
	v_cvt_pk_bf16_f32 v118, v66, v67
	v_cvt_pk_bf16_f32 v119, v68, v69
	ds_read_b64_tr_b16 v[66:67], v172 offset:30720
	ds_read_b64_tr_b16 v[68:69], v172 offset:31232
	v_mfma_f32_32x32x16_bf16 v[34:49], v[138:141], v[102:105], v[34:49]
	v_add_f32_e32 v110, v72, v110
	v_add_f32_e32 v110, v73, v110
	v_add_f32_e32 v110, v74, v110
	v_add_f32_e32 v110, v75, v110
	v_cvt_pk_bf16_f32 v120, v70, v71
	v_cvt_pk_bf16_f32 v121, v72, v73
	ds_read_b64_tr_b16 v[70:71], v172 offset:27648
	ds_read_b64_tr_b16 v[72:73], v172 offset:28160
	v_mfma_f32_32x32x16_bf16 v[50:65], v[134:137], v[98:101], v[50:65]
	v_add_f32_e32 v110, v76, v110
	v_add_f32_e32 v110, v77, v110
	v_add_f32_e32 v110, v78, v110
	v_add_f32_e32 v134, v79, v110
	v_cvt_pk_bf16_f32 v110, v74, v75
	v_cvt_pk_bf16_f32 v111, v76, v77
	ds_read_b64_tr_b16 v[74:75], v172 offset:31744
	ds_read_b64_tr_b16 v[76:77], v172 offset:32256
	v_mfma_f32_32x32x16_bf16 v[34:49], v[130:133], v[98:101], v[34:49]
	v_add_f32_e32 v112, v80, v134
	v_add_f32_e32 v112, v81, v112
	v_add_f32_e32 v130, 0, v112
	v_cvt_pk_bf16_f32 v112, v78, v79
	v_cvt_pk_bf16_f32 v113, v80, v81
	s_add_i32 s34, s28, s84
	s_mov_b32 s35, m0
	s_mov_b32 m0, s34
	s_nop 0
	global_load_lds_dwordx4 v191, s[12:13]
	s_mov_b32 m0, s35
	s_add_i32 s34, s27, s85
	s_mov_b32 s35, m0
	s_mov_b32 m0, s34
	s_nop 0
	global_load_lds_dwordx4 v192, s[10:11]
	s_mov_b32 m0, s35
	v_add_f32_e32 v243, v167, v130
	s_add_i32 s31, s31, 2
	s_waitcnt lgkmcnt(14)
	v_mfma_f32_32x32x16_bf16 v[2:17], v[126:129], v[158:161], v[2:17]
	v_exp_f32_e32 v50, v50
	v_exp_f32_e32 v51, v51
	v_exp_f32_e32 v52, v52
	v_exp_f32_e32 v53, v53
	s_waitcnt lgkmcnt(12)
	v_mfma_f32_32x32x16_bf16 v[18:33], v[126:129], v[82:85], v[18:33]
	v_exp_f32_e32 v54, v54
	v_exp_f32_e32 v55, v55
	v_exp_f32_e32 v56, v56
	v_exp_f32_e32 v57, v57
	v_add_u32_e32 v78, s27, v193
	ds_read_b128 v[158:161], v78
	ds_read_b128 v[154:157], v78 offset:512
	s_waitcnt lgkmcnt(12)
	v_mfma_f32_32x32x16_bf16 v[2:17], v[122:125], v[86:89], v[2:17]
	v_exp_f32_e32 v58, v58
	v_exp_f32_e32 v59, v59
	v_exp_f32_e32 v60, v60
	v_exp_f32_e32 v61, v61
	ds_read_b128 v[150:153], v78 offset:2048
	ds_read_b128 v[146:149], v78 offset:2560
	s_waitcnt lgkmcnt(12)
	v_mfma_f32_32x32x16_bf16 v[18:33], v[122:125], v[90:93], v[18:33]
	v_exp_f32_e32 v62, v62
	v_exp_f32_e32 v63, v63
	v_exp_f32_e32 v64, v64
	v_exp_f32_e32 v65, v65
	ds_read_b128 v[142:145], v78 offset:4096
	ds_read_b128 v[138:141], v78 offset:4608
	s_waitcnt lgkmcnt(12)
	v_mfma_f32_32x32x16_bf16 v[2:17], v[118:121], v[94:97], v[2:17]
	v_exp_f32_e32 v34, v34
	v_exp_f32_e32 v35, v35
	v_exp_f32_e32 v36, v36
	v_exp_f32_e32 v37, v37
	ds_read_b128 v[134:137], v78 offset:6144
	ds_read_b128 v[130:133], v78 offset:6656
	s_waitcnt lgkmcnt(12)
	v_mfma_f32_32x32x16_bf16 v[18:33], v[118:121], v[66:69], v[18:33]
	v_exp_f32_e32 v38, v38
	v_exp_f32_e32 v39, v39
	v_exp_f32_e32 v40, v40
	v_exp_f32_e32 v41, v41
	s_waitcnt lgkmcnt(10)
	v_mfma_f32_32x32x16_bf16 v[2:17], v[110:113], v[70:73], v[2:17]
	v_exp_f32_e32 v42, v42
	v_exp_f32_e32 v43, v43
	v_exp_f32_e32 v44, v44
	v_exp_f32_e32 v45, v45
	s_waitcnt lgkmcnt(8)
	v_mfma_f32_32x32x16_bf16 v[18:33], v[110:113], v[74:77], v[18:33]
	v_exp_f32_e32 v46, v46
	v_exp_f32_e32 v47, v47
	v_exp_f32_e32 v48, v48
	v_exp_f32_e32 v49, v49
	s_add_i32 s34, s27, 0x2000
	s_cmpk_lg_i32 s27, 0x4000
	s_cselect_b32 s34, s34, 0
	s_add_u32 s10, s10, 0xc0000
	s_addc_u32 s11, s11, 0
	s_waitcnt vmcnt(2) lgkmcnt(0)
	s_barrier
	s_add_u32 s12, s12, 0xc0000
	s_addc_u32 s13, s13, 0
	v_add_u32_e32 v166, 0x200, v166
	s_cmp_ge_i32 s31, s30
	s_mov_b32 s35, s28
	s_cbranch_scc0 .LBB0_672
	v_readlane_b32 s30, v253, 58
	s_add_i32 s10, s31, 1
	s_cmp_ge_i32 s10, s25
	s_cbranch_scc0 .LBB0_676
